# grid-barrier poll loops: s_sleep 1 replaced by s_nop 7 (tighter spin); rest identical to v34
# baseline (speedup 1.0000x reference)
; #define GRID_SYNC() do { xcd_barrier(xbar); } while (0)
; __global__ void __launch_bounds__(512) fwd_megakernel(KArgs a) {
;     ...
;     if (a.use_cg_sync) { grid.sync(); __builtin_amdgcn_fence(__ATOMIC_ACQUIRE, "agent"); } else GRID_SYNC();
.LBB0_105:
	s_nop 7
	global_load_dword v2, v0, s[4:5] offset:32 sc1
	s_waitcnt vmcnt(0)
	v_and_b32_e32 v2, 0xffff0000, v2
	v_cmp_ne_u32_e32 vcc, v2, v1
	s_or_b64 s[6:7], vcc, s[6:7]
	s_andn2_b64 exec, exec, s[6:7]
	s_cbranch_execnz .LBB0_105

; __device__ __forceinline__ unsigned xb_ld(unsigned* p)              { return __hip_atomic_load(p, __ATOMIC_RELAXED, __HIP_MEMORY_SCOPE_AGENT); }
; __device__ __forceinline__ void xcd_barrier_complete(unsigned* bar, unsigned x, unsigned& nloc, unsigned& nx) {
;     const unsigned G = gridDim.x * gridDim.y * gridDim.z;
;     unsigned sum, cnt, mine, sp = 0u;
;     for (;;) {
;         sum = 0u; cnt = 0u; mine = 0u;
; #pragma unroll
;         for (unsigned j = 0; j < 16; ++j) { const unsigned c = xb_ld(&bar[XB_XCNT(j)]); sum += c; cnt += (c > 0u) ? 1u : 0u; mine = (j == x) ? c : mine; }
;         if (sum == G) break;
;         __builtin_amdgcn_s_sleep(1);
;         if ((++sp & 255u) == 0u) { if (xb_ld(&bar[XB_TMO])) break; if (sp > XB_SPIN_CAP) { atomicAdd(&bar[XB_TMO], 1u); break; } }
;     }
;     nloc = mine > 0u ? mine : 1u; nx = cnt > 0u ? cnt : 1u;
; }
.LBB0_113:
	global_load_dword v15, v16, s[6:7] sc1
	s_waitcnt lgkmcnt(0)
	global_load_dword v0, v16, s[8:9] sc1
	global_load_dword v1, v16, s[10:11] sc1
	global_load_dword v2, v16, s[12:13] sc1
	global_load_dword v3, v16, s[14:15] sc1
	global_load_dword v4, v16, s[16:17] sc1
	global_load_dword v5, v16, s[18:19] sc1
	global_load_dword v6, v16, s[20:21] sc1
	global_load_dword v7, v16, s[22:23] sc1
	global_load_dword v8, v16, s[24:25] sc1
	global_load_dword v9, v16, s[28:29] sc1
	global_load_dword v10, v16, s[30:31] sc1
	global_load_dword v11, v16, s[34:35] sc1
	global_load_dword v12, v16, s[36:37] sc1
	global_load_dword v13, v16, s[38:39] sc1
	global_load_dword v14, v16, s[40:41] sc1
	s_mov_b64 s[42:43], -1
	s_mov_b64 s[44:45], -1
	s_waitcnt vmcnt(14)
	v_add_u32_e32 v17, v0, v15
	s_waitcnt vmcnt(13)
	v_add_u32_e32 v17, v17, v1
	s_waitcnt vmcnt(12)
	v_add_u32_e32 v17, v17, v2
	s_waitcnt vmcnt(11)
	v_add_u32_e32 v17, v17, v3
	s_waitcnt vmcnt(10)
	v_add_u32_e32 v17, v17, v4
	s_waitcnt vmcnt(9)
	v_add_u32_e32 v17, v17, v5
	s_waitcnt vmcnt(8)
	v_add_u32_e32 v17, v17, v6
	s_waitcnt vmcnt(7)
	v_add_u32_e32 v17, v17, v7
	s_waitcnt vmcnt(6)
	v_add_u32_e32 v17, v17, v8
	s_waitcnt vmcnt(5)
	v_add_u32_e32 v17, v17, v9
	s_waitcnt vmcnt(4)
	v_add_u32_e32 v17, v17, v10
	s_waitcnt vmcnt(3)
	v_add_u32_e32 v17, v17, v11
	s_waitcnt vmcnt(2)
	v_add_u32_e32 v17, v17, v12
	s_waitcnt vmcnt(1)
	v_add_u32_e32 v17, v17, v13
	s_waitcnt vmcnt(0)
	v_add_u32_e32 v17, v17, v14
	v_cmp_eq_u32_e32 vcc, s3, v17
	s_cbranch_vccnz .LBB0_112
	s_and_b32 s42, s33, 0xff
	s_cmp_eq_u32 s42, 0
	s_mov_b64 s[42:43], -1
	s_mov_b64 s[46:47], -1
	s_nop 7
	s_cbranch_scc1 .LBB0_117
	s_and_b64 vcc, exec, s[46:47]
	s_cbranch_vccz .LBB0_112

; __device__ __forceinline__ unsigned xb_ld(unsigned* p)              { return __hip_atomic_load(p, __ATOMIC_RELAXED, __HIP_MEMORY_SCOPE_AGENT); }
; __device__ __forceinline__ unsigned xb_add(unsigned* p, unsigned v) { return __hip_atomic_fetch_add(p, v, __ATOMIC_RELAXED, __HIP_MEMORY_SCOPE_AGENT); }
; #define XB_SPIN(cond, bar) do { unsigned _sp = 0; while (cond) { __builtin_amdgcn_s_sleep(1); \
;     if ((++_sp & 255u) == 0u) { if (xb_ld(&(bar)[XB_TMO])) break; if (_sp > XB_SPIN_CAP) { atomicAdd(&(bar)[XB_TMO], 1u); break; } } } } while (0)
; __device__ __forceinline__ void xcd_barrier(const XcdBarrier& b) {
;     ...
;             const unsigned og = xb_add(&bar[XB_TOP], 1u);
;             const unsigned tg = og / nx;
;             if (og + 1u == (tg + 1u) * nx) xb_add(&bar[XB_TOPGEN], 1u);
;             else XB_SPIN(xb_ld(&bar[XB_TOPGEN]) == tg, bar);
.LBB0_131:
	s_and_b32 s20, s3, 0xff
	s_mov_b64 s[18:19], -1
	s_cmp_lg_u32 s20, 0
	s_mov_b64 s[22:23], -1
	s_nop 7
	s_cbranch_scc0 .LBB0_134
	s_and_b64 vcc, exec, s[22:23]
	s_cbranch_vccz .LBB0_130

; __device__ __forceinline__ unsigned xb_ld(unsigned* p)              { return __hip_atomic_load(p, __ATOMIC_RELAXED, __HIP_MEMORY_SCOPE_AGENT); }
; #define XB_SPIN(cond, bar) do { unsigned _sp = 0; while (cond) { __builtin_amdgcn_s_sleep(1); \
;     if ((++_sp & 255u) == 0u) { if (xb_ld(&(bar)[XB_TMO])) break; if (_sp > XB_SPIN_CAP) { atomicAdd(&(bar)[XB_TMO], 1u); break; } } } } while (0)
; __device__ __forceinline__ void xcd_barrier(const XcdBarrier& b) {
;     ...
;         } else {
;             XB_SPIN(xb_ld(&bar[XB_XGEN(b.x)]) == gen, bar);
.LBB0_148:
	s_and_b32 s18, s3, 0xff
	s_cmp_lg_u32 s18, 0
	s_mov_b64 s[20:21], -1
	s_nop 7
	s_cbranch_scc0 .LBB0_151
	s_mov_b64 s[22:23], -1
	s_and_b64 vcc, exec, s[20:21]
	s_cbranch_vccz .LBB0_147

; __device__ __forceinline__ unsigned xb_ld(unsigned* p)              { return __hip_atomic_load(p, __ATOMIC_RELAXED, __HIP_MEMORY_SCOPE_AGENT); }
; __device__ __forceinline__ void xcd_barrier_complete(unsigned* bar, unsigned x, unsigned& nloc, unsigned& nx) {
;     const unsigned G = gridDim.x * gridDim.y * gridDim.z;
;     unsigned sum, cnt, mine, sp = 0u;
;     for (;;) {
;         sum = 0u; cnt = 0u; mine = 0u;
; #pragma unroll
;         for (unsigned j = 0; j < 16; ++j) { const unsigned c = xb_ld(&bar[XB_XCNT(j)]); sum += c; cnt += (c > 0u) ? 1u : 0u; mine = (j == x) ? c : mine; }
;         if (sum == G) break;
;         __builtin_amdgcn_s_sleep(1);
;         if ((++sp & 255u) == 0u) { if (xb_ld(&bar[XB_TMO])) break; if (sp > XB_SPIN_CAP) { atomicAdd(&bar[XB_TMO], 1u); break; } }
;     }
;     nloc = mine > 0u ? mine : 1u; nx = cnt > 0u ? cnt : 1u;
; }
.LBB0_416:
	v_readlane_b32 s4, v252, 44
	v_readlane_b32 s5, v252, 45
	global_load_dword v2, v181, s[74:75] sc1
	s_waitcnt lgkmcnt(0)
	global_load_dword v0, v181, s[72:73] sc1
	global_load_dword v1, v181, s[64:65] sc1
	s_mov_b64 s[6:7], -1
	s_waitcnt vmcnt(1)
	v_add_u32_e32 v16, v0, v2
	global_load_dword v3, v181, s[4:5] sc1
	v_readlane_b32 s4, v252, 46
	v_readlane_b32 s5, v252, 47
	s_waitcnt vmcnt(1)
	v_add_u32_e32 v16, v16, v1
	s_waitcnt vmcnt(0)
	v_add_u32_e32 v16, v16, v3
	s_nop 0
	global_load_dword v4, v181, s[4:5] sc1
	v_readlane_b32 s4, v252, 48
	v_readlane_b32 s5, v252, 49
	s_waitcnt vmcnt(0)
	v_add_u32_e32 v16, v16, v4
	s_nop 2
	global_load_dword v5, v181, s[4:5] sc1
	v_readlane_b32 s4, v252, 50
	v_readlane_b32 s5, v252, 51
	s_waitcnt vmcnt(0)
	v_add_u32_e32 v16, v16, v5
	s_nop 2
	global_load_dword v6, v181, s[4:5] sc1
	v_readlane_b32 s4, v252, 52
	v_readlane_b32 s5, v252, 53
	s_waitcnt vmcnt(0)
	v_add_u32_e32 v16, v16, v6
	s_nop 2
	global_load_dword v7, v181, s[4:5] sc1
	v_readlane_b32 s4, v252, 54
	v_readlane_b32 s5, v252, 55
	s_waitcnt vmcnt(0)
	v_add_u32_e32 v16, v16, v7
	s_nop 2
	global_load_dword v8, v181, s[4:5] sc1
	v_readlane_b32 s4, v252, 56
	v_readlane_b32 s5, v252, 57
	s_waitcnt vmcnt(0)
	v_add_u32_e32 v16, v16, v8
	s_nop 2
	global_load_dword v9, v181, s[4:5] sc1
	v_readlane_b32 s4, v252, 58
	v_readlane_b32 s5, v252, 59
	s_waitcnt vmcnt(0)
	v_add_u32_e32 v16, v16, v9
	s_nop 2
	global_load_dword v10, v181, s[4:5] sc1
	v_readlane_b32 s4, v252, 60
	v_readlane_b32 s5, v252, 61
	s_waitcnt vmcnt(0)
	v_add_u32_e32 v16, v16, v10
	s_nop 2
	global_load_dword v11, v181, s[4:5] sc1
	v_readlane_b32 s4, v252, 62
	v_readlane_b32 s5, v252, 63
	s_waitcnt vmcnt(0)
	v_add_u32_e32 v16, v16, v11
	s_nop 2
	global_load_dword v12, v181, s[4:5] sc1
	v_readlane_b32 s4, v253, 0
	v_readlane_b32 s5, v253, 1
	s_waitcnt vmcnt(0)
	v_add_u32_e32 v16, v16, v12
	s_nop 2
	global_load_dword v13, v181, s[4:5] sc1
	v_readlane_b32 s4, v253, 2
	v_readlane_b32 s5, v253, 3
	s_waitcnt vmcnt(0)
	v_add_u32_e32 v16, v16, v13
	s_nop 2
	global_load_dword v14, v181, s[4:5] sc1
	v_readlane_b32 s4, v253, 4
	v_readlane_b32 s5, v253, 5
	s_waitcnt vmcnt(0)
	v_add_u32_e32 v16, v16, v14
	s_nop 2
	global_load_dword v15, v181, s[4:5] sc1
	s_mov_b64 s[4:5], -1
	s_waitcnt vmcnt(0)
	v_add_u32_e32 v16, v16, v15
	v_cmp_eq_u32_e32 vcc, s85, v16
	s_cbranch_vccnz .LBB0_415
	s_and_b32 s4, s13, 0xff
	s_cmp_eq_u32 s4, 0
	s_mov_b64 s[4:5], -1
	s_mov_b64 s[28:29], -1
	s_nop 7
	s_cbranch_scc1 .LBB0_420
	s_and_b64 vcc, exec, s[28:29]
	s_cbranch_vccz .LBB0_415

; __device__ __forceinline__ unsigned xb_ld(unsigned* p)              { return __hip_atomic_load(p, __ATOMIC_RELAXED, __HIP_MEMORY_SCOPE_AGENT); }
; #define XB_SPIN(cond, bar) do { unsigned _sp = 0; while (cond) { __builtin_amdgcn_s_sleep(1); \
;     if ((++_sp & 255u) == 0u) { if (xb_ld(&(bar)[XB_TMO])) break; if (_sp > XB_SPIN_CAP) { atomicAdd(&(bar)[XB_TMO], 1u); break; } } } } while (0)
; __device__ __forceinline__ void xcd_barrier(const XcdBarrier& b) {
;     ...
;             else XB_SPIN(xb_ld(&bar[XB_TOPGEN]) == tg, bar);
.LBB0_434:
	s_and_b32 s15, s13, 0xff
	s_mov_b64 s[38:39], -1
	s_cmp_lg_u32 s15, 0
	s_mov_b64 s[42:43], -1
	s_nop 7
	s_cbranch_scc0 .LBB0_437
	s_and_b64 vcc, exec, s[42:43]
	s_cbranch_vccz .LBB0_433

; __device__ __forceinline__ unsigned xb_ld(unsigned* p)              { return __hip_atomic_load(p, __ATOMIC_RELAXED, __HIP_MEMORY_SCOPE_AGENT); }
; __device__ __forceinline__ void xcd_barrier_complete(unsigned* bar, unsigned x, unsigned& nloc, unsigned& nx) {
;     const unsigned G = gridDim.x * gridDim.y * gridDim.z;
;     unsigned sum, cnt, mine, sp = 0u;
;     for (;;) {
;         sum = 0u; cnt = 0u; mine = 0u;
; #pragma unroll
;         for (unsigned j = 0; j < 16; ++j) { const unsigned c = xb_ld(&bar[XB_XCNT(j)]); sum += c; cnt += (c > 0u) ? 1u : 0u; mine = (j == x) ? c : mine; }
;         if (sum == G) break;
;         __builtin_amdgcn_s_sleep(1);
;         if ((++sp & 255u) == 0u) { if (xb_ld(&bar[XB_TMO])) break; if (sp > XB_SPIN_CAP) { atomicAdd(&bar[XB_TMO], 1u); break; } }
;     }
;     nloc = mine > 0u ? mine : 1u; nx = cnt > 0u ? cnt : 1u;
; }
.LBB0_825:
	v_readlane_b32 s6, v252, 44
	v_readlane_b32 s7, v252, 45
	global_load_dword v2, v181, s[74:75] sc1
	s_waitcnt lgkmcnt(0)
	global_load_dword v0, v181, s[72:73] sc1
	global_load_dword v1, v181, s[64:65] sc1
	s_mov_b64 s[28:29], -1
	s_waitcnt vmcnt(1)
	v_add_u32_e32 v16, v0, v2
	global_load_dword v3, v181, s[6:7] sc1
	v_readlane_b32 s6, v252, 46
	v_readlane_b32 s7, v252, 47
	s_waitcnt vmcnt(1)
	v_add_u32_e32 v16, v16, v1
	s_waitcnt vmcnt(0)
	v_add_u32_e32 v16, v16, v3
	s_nop 0
	global_load_dword v4, v181, s[6:7] sc1
	v_readlane_b32 s6, v252, 48
	v_readlane_b32 s7, v252, 49
	s_waitcnt vmcnt(0)
	v_add_u32_e32 v16, v16, v4
	s_nop 2
	global_load_dword v5, v181, s[6:7] sc1
	v_readlane_b32 s6, v252, 50
	v_readlane_b32 s7, v252, 51
	s_waitcnt vmcnt(0)
	v_add_u32_e32 v16, v16, v5
	s_nop 2
	global_load_dword v6, v181, s[6:7] sc1
	v_readlane_b32 s6, v252, 52
	v_readlane_b32 s7, v252, 53
	s_waitcnt vmcnt(0)
	v_add_u32_e32 v16, v16, v6
	s_nop 2
	global_load_dword v7, v181, s[6:7] sc1
	v_readlane_b32 s6, v252, 54
	v_readlane_b32 s7, v252, 55
	s_waitcnt vmcnt(0)
	v_add_u32_e32 v16, v16, v7
	s_nop 2
	global_load_dword v8, v181, s[6:7] sc1
	v_readlane_b32 s6, v252, 56
	v_readlane_b32 s7, v252, 57
	s_waitcnt vmcnt(0)
	v_add_u32_e32 v16, v16, v8
	s_nop 2
	global_load_dword v9, v181, s[6:7] sc1
	v_readlane_b32 s6, v252, 58
	v_readlane_b32 s7, v252, 59
	s_waitcnt vmcnt(0)
	v_add_u32_e32 v16, v16, v9
	s_nop 2
	global_load_dword v10, v181, s[6:7] sc1
	v_readlane_b32 s6, v252, 60
	v_readlane_b32 s7, v252, 61
	s_waitcnt vmcnt(0)
	v_add_u32_e32 v16, v16, v10
	s_nop 2
	global_load_dword v11, v181, s[6:7] sc1
	v_readlane_b32 s6, v252, 62
	v_readlane_b32 s7, v252, 63
	s_waitcnt vmcnt(0)
	v_add_u32_e32 v16, v16, v11
	s_nop 2
	global_load_dword v12, v181, s[6:7] sc1
	v_readlane_b32 s6, v253, 0
	v_readlane_b32 s7, v253, 1
	s_waitcnt vmcnt(0)
	v_add_u32_e32 v16, v16, v12
	s_nop 2
	global_load_dword v13, v181, s[6:7] sc1
	v_readlane_b32 s6, v253, 2
	v_readlane_b32 s7, v253, 3
	s_waitcnt vmcnt(0)
	v_add_u32_e32 v16, v16, v13
	s_nop 2
	global_load_dword v14, v181, s[6:7] sc1
	v_readlane_b32 s6, v253, 4
	v_readlane_b32 s7, v253, 5
	s_waitcnt vmcnt(0)
	v_add_u32_e32 v16, v16, v14
	s_nop 2
	global_load_dword v15, v181, s[6:7] sc1
	s_mov_b64 s[6:7], -1
	s_waitcnt vmcnt(0)
	v_add_u32_e32 v16, v16, v15
	v_cmp_eq_u32_e32 vcc, s85, v16
	s_cbranch_vccnz .LBB0_824
	s_and_b32 s6, s13, 0xff
	s_cmp_eq_u32 s6, 0
	s_mov_b64 s[6:7], -1
	s_mov_b64 s[30:31], -1
	s_nop 7
	s_cbranch_scc1 .LBB0_829
	s_and_b64 vcc, exec, s[30:31]
	s_cbranch_vccz .LBB0_824

; __device__ __forceinline__ unsigned xb_ld(unsigned* p)              { return __hip_atomic_load(p, __ATOMIC_RELAXED, __HIP_MEMORY_SCOPE_AGENT); }
; #define XB_SPIN(cond, bar) do { unsigned _sp = 0; while (cond) { __builtin_amdgcn_s_sleep(1); \
;     if ((++_sp & 255u) == 0u) { if (xb_ld(&(bar)[XB_TMO])) break; if (_sp > XB_SPIN_CAP) { atomicAdd(&(bar)[XB_TMO], 1u); break; } } } } while (0)
; __device__ __forceinline__ void xcd_barrier(const XcdBarrier& b) {
;     ...
;             XB_SPIN(xb_ld(&bar[XB_XGEN(b.x)]) == gen, bar);
.LBB0_843:
	s_and_b32 s15, s13, 0xff
	s_mov_b64 s[40:41], -1
	s_cmp_lg_u32 s15, 0
	s_mov_b64 s[44:45], -1
	s_nop 7
	s_cbranch_scc0 .LBB0_846
	s_and_b64 vcc, exec, s[44:45]
	s_cbranch_vccz .LBB0_842
